# stack2 + phase-7 conversion items and zero-fill job dealt starting at workgroup 88 (halo workgroups get one item)
# speedup vs baseline: 1.0125x; 1.0042x over previous
; __global__ void __launch_bounds__(NWAVES * 64, 2) fwd_mega(Args args) {
;     ...
;             for (int i = gwu * 64 + lane; i < 1024 * 16; i += NGWU * 64) { const int n = i >> 4, c = i & 15; *(v4u*)(Wukv + (size_t)n * 256 + 128 + c * 8) = (v4u){0u, 0u, 0u, 0u}; }
.LBB0_1037:
	v_lshl_or_b32 v1, s3, 6, v145
	v_writelane_b32 v253, s99, 0
	s_movk_i32 s0, 0x4000
	v_cmp_gt_i32_e32 vcc, s0, v1
	s_and_saveexec_b64 s[6:7], vcc
	v_readlane_b32 s2, v253, 14
	v_readlane_b32 s3, v253, 15
	s_cbranch_execz .LBB0_1040
	v_readlane_b32 s0, v253, 4
	v_readlane_b32 s1, v253, 5
	s_load_dword s0, s[0:1], 0x168
	v_mov_b32_e32 v3, 0
	v_lshlrev_b32_e32 v4, 3, v1
	s_mov_b64 s[8:9], 0
	v_mov_b32_e32 v6, v3
	s_waitcnt lgkmcnt(0)
	s_lshl_b32 s0, s0, 12
	v_mov_b32_e32 v7, v3
	v_mov_b32_e32 v8, v3
	v_mov_b32_e32 v9, v3
	s_movk_i32 s1, 0x3fff
